# lever 2: layer-0 gres16 epilogue - the 16 nt residual loads issued together with counted waits (was a 16-step serial ladder)
# speedup vs baseline: 1.0153x; 1.0028x over previous
.LBB0_749:
	v_lshl_add_u32 v66, s12, 7, v99
	v_ashrrev_i32_e32 v64, 31, v66
	v_cmp_gt_i32_e32 vcc, s93, v66
	v_readlane_b32 s52, v254, 39
	v_add_u32_e32 v68, 0xffffc000, v66
	v_cndmask_b32_e32 v67, 0, v64, vcc
	v_readlane_b32 s53, v254, 40
	v_readlane_b32 s54, v254, 41
	v_readlane_b32 s55, v254, 42
	v_cndmask_b32_e32 v68, v68, v66, vcc
	v_mov_b32_e32 v69, v67
	v_mov_b32_e32 v64, s55
	v_mov_b32_e32 v78, s53
	v_mov_b32_e32 v79, s54
	v_mov_b32_e32 v80, s52
	v_cndmask_b32_e32 v71, v64, v78, vcc
	v_cndmask_b32_e32 v70, v79, v80, vcc
	v_lshlrev_b64 v[68:69], 12, v[68:69]
	v_lshl_add_u64 v[68:69], v[70:71], 0, v[68:69]
	v_lshl_or_b32 v70, s10, 7, v98
	v_ashrrev_i32_e32 v71, 31, v70
	v_lshlrev_b64 v[72:73], 2, v[70:71]
	v_lshl_add_u64 v[74:75], v[68:69], 0, v[72:73]
	s_waitcnt vmcnt(0)
	s_barrier
	v_readlane_b32 s12, v254, 3
	v_lshlrev_b64 v[76:77], 12, v[66:67]
	v_readlane_b32 s26, v254, 17
	v_readlane_b32 s27, v254, 18
	s_add_i32 s3, s3, s91
	s_add_i32 s92, s92, s28
	v_lshl_add_u64 v[76:77], s[26:27], 0, v[76:77]
	v_lshl_add_u64 v[76:77], v[76:77], 0, v[72:73]
	s_cmpk_gt_i32 s3, 0x87
	v_readlane_b32 s56, v254, 43
	v_readlane_b32 s57, v254, 44
	v_readlane_b32 s58, v254, 45
	v_readlane_b32 s59, v254, 46
	v_readlane_b32 s60, v254, 47
	v_readlane_b32 s61, v254, 48
	v_readlane_b32 s62, v254, 49
	v_readlane_b32 s63, v254, 50
	v_readlane_b32 s64, v254, 51
	v_readlane_b32 s65, v254, 52
	v_readlane_b32 s66, v254, 53
	v_readlane_b32 s67, v254, 54
	v_readlane_b32 s13, v254, 4
	v_readlane_b32 s14, v254, 5
	v_readlane_b32 s15, v254, 6
	v_readlane_b32 s16, v254, 7
	v_readlane_b32 s17, v254, 8
	v_readlane_b32 s18, v254, 9
	v_readlane_b32 s19, v254, 10
	v_readlane_b32 s20, v254, 11
	v_readlane_b32 s21, v254, 12
	v_readlane_b32 s22, v254, 13
	v_readlane_b32 s23, v254, 14
	v_readlane_b32 s24, v254, 15
	v_readlane_b32 s25, v254, 16
	v_or_b32_e32 v184, 16, v66
	v_cmp_gt_i32_e32 vcc, s93, v184
	v_add_u32_e32 v170, 0xffffc010, v66
	v_mov_b32_e32 v171, 0
	v_cndmask_b32_e32 v170, v170, v184, vcc
	v_cndmask_b32_e32 v187, v64, v78, vcc
	v_cndmask_b32_e32 v186, v79, v80, vcc
	v_lshlrev_b64 v[170:171], 12, v[170:171]
	v_lshl_add_u64 v[170:171], v[186:187], 0, v[170:171]
	v_lshl_add_u64 v[170:171], v[170:171], 0, v[72:73]
	v_mov_b32_e32 v178, v184
	v_mov_b32_e32 v179, 0
	v_lshlrev_b64 v[178:179], 12, v[178:179]
	v_lshl_add_u64 v[178:179], s[26:27], 0, v[178:179]
	v_lshl_add_u64 v[178:179], v[178:179], 0, v[72:73]
	v_or_b32_e32 v184, 32, v66
	v_cmp_gt_i32_e32 vcc, s93, v184
	v_add_u32_e32 v172, 0xffffc020, v66
	v_mov_b32_e32 v173, 0
	v_cndmask_b32_e32 v172, v172, v184, vcc
	v_cndmask_b32_e32 v187, v64, v78, vcc
	v_cndmask_b32_e32 v186, v79, v80, vcc
	v_lshlrev_b64 v[172:173], 12, v[172:173]
	v_lshl_add_u64 v[172:173], v[186:187], 0, v[172:173]
	v_lshl_add_u64 v[172:173], v[172:173], 0, v[72:73]
	v_mov_b32_e32 v180, v184
	v_mov_b32_e32 v181, 0
	v_lshlrev_b64 v[180:181], 12, v[180:181]
	v_lshl_add_u64 v[180:181], s[26:27], 0, v[180:181]
	v_lshl_add_u64 v[180:181], v[180:181], 0, v[72:73]
	v_or_b32_e32 v184, 48, v66
	v_cmp_gt_i32_e32 vcc, s93, v184
	v_add_u32_e32 v176, 0xffffc030, v66
	v_mov_b32_e32 v177, 0
	v_cndmask_b32_e32 v176, v176, v184, vcc
	v_cndmask_b32_e32 v187, v64, v78, vcc
	v_cndmask_b32_e32 v186, v79, v80, vcc
	v_lshlrev_b64 v[176:177], 12, v[176:177]
	v_lshl_add_u64 v[176:177], v[186:187], 0, v[176:177]
	v_lshl_add_u64 v[176:177], v[176:177], 0, v[72:73]
	v_mov_b32_e32 v182, v184
	v_mov_b32_e32 v183, 0
	v_lshlrev_b64 v[182:183], 12, v[182:183]
	v_lshl_add_u64 v[182:183], s[26:27], 0, v[182:183]
	v_lshl_add_u64 v[182:183], v[182:183], 0, v[72:73]
	global_load_dwordx4 v[82:85], v[74:75], off nt
	global_load_dwordx4 v[86:89], v[74:75], off offset:64 nt
	global_load_dwordx4 v[90:93], v[74:75], off offset:128 nt
	global_load_dwordx4 v[94:97], v[74:75], off offset:192 nt
	global_load_dwordx4 v[122:125], v[170:171], off nt
	global_load_dwordx4 v[126:129], v[170:171], off offset:64 nt
	global_load_dwordx4 v[130:133], v[170:171], off offset:128 nt
	global_load_dwordx4 v[134:137], v[170:171], off offset:192 nt
	global_load_dwordx4 v[138:141], v[172:173], off nt
	global_load_dwordx4 v[142:145], v[172:173], off offset:64 nt
	global_load_dwordx4 v[146:149], v[172:173], off offset:128 nt
	global_load_dwordx4 v[150:153], v[172:173], off offset:192 nt
	global_load_dwordx4 v[154:157], v[176:177], off nt
	global_load_dwordx4 v[158:161], v[176:177], off offset:64 nt
	global_load_dwordx4 v[162:165], v[176:177], off offset:128 nt
	global_load_dwordx4 v[166:169], v[176:177], off offset:192 nt
	s_waitcnt vmcnt(15)
	v_pk_add_f32 v[60:61], v[60:61], v[82:83]
	v_pk_add_f32 v[62:63], v[62:63], v[84:85]
	s_waitcnt vmcnt(14)
	v_pk_add_f32 v[56:57], v[56:57], v[86:87]
	v_pk_add_f32 v[58:59], v[58:59], v[88:89]
	s_waitcnt vmcnt(13)
	v_pk_add_f32 v[52:53], v[52:53], v[90:91]
	v_pk_add_f32 v[54:55], v[54:55], v[92:93]
	s_waitcnt vmcnt(12)
	v_pk_add_f32 v[48:49], v[48:49], v[94:95]
	v_pk_add_f32 v[50:51], v[50:51], v[96:97]
	s_waitcnt vmcnt(11)
	v_pk_add_f32 v[44:45], v[44:45], v[122:123]
	v_pk_add_f32 v[46:47], v[46:47], v[124:125]
	s_waitcnt vmcnt(10)
	v_pk_add_f32 v[40:41], v[40:41], v[126:127]
	v_pk_add_f32 v[42:43], v[42:43], v[128:129]
	s_waitcnt vmcnt(9)
	v_pk_add_f32 v[36:37], v[36:37], v[130:131]
	v_pk_add_f32 v[38:39], v[38:39], v[132:133]
	s_waitcnt vmcnt(8)
	v_pk_add_f32 v[32:33], v[32:33], v[134:135]
	v_pk_add_f32 v[34:35], v[34:35], v[136:137]
	s_waitcnt vmcnt(7)
	v_pk_add_f32 v[28:29], v[28:29], v[138:139]
	v_pk_add_f32 v[30:31], v[30:31], v[140:141]
	s_waitcnt vmcnt(6)
	v_pk_add_f32 v[24:25], v[24:25], v[142:143]
	v_pk_add_f32 v[26:27], v[26:27], v[144:145]
	s_waitcnt vmcnt(5)
	v_pk_add_f32 v[20:21], v[20:21], v[146:147]
	v_pk_add_f32 v[22:23], v[22:23], v[148:149]
	s_waitcnt vmcnt(4)
	v_pk_add_f32 v[16:17], v[16:17], v[150:151]
	v_pk_add_f32 v[18:19], v[18:19], v[152:153]
	s_waitcnt vmcnt(3)
	v_pk_add_f32 v[12:13], v[12:13], v[154:155]
	v_pk_add_f32 v[14:15], v[14:15], v[156:157]
	s_waitcnt vmcnt(2)
	v_pk_add_f32 v[8:9], v[8:9], v[158:159]
	v_pk_add_f32 v[10:11], v[10:11], v[160:161]
	s_waitcnt vmcnt(1)
	v_pk_add_f32 v[4:5], v[4:5], v[162:163]
	v_pk_add_f32 v[6:7], v[6:7], v[164:165]
	s_waitcnt vmcnt(0)
	v_pk_add_f32 v[0:1], v[0:1], v[166:167]
	v_pk_add_f32 v[2:3], v[2:3], v[168:169]
	global_store_dwordx4 v[76:77], v[60:63], off
	global_store_dwordx4 v[76:77], v[56:59], off offset:64
	global_store_dwordx4 v[76:77], v[52:55], off offset:128
	global_store_dwordx4 v[76:77], v[48:51], off offset:192
	global_store_dwordx4 v[178:179], v[44:47], off
	global_store_dwordx4 v[178:179], v[40:43], off offset:64
	global_store_dwordx4 v[178:179], v[36:39], off offset:128
	global_store_dwordx4 v[178:179], v[32:35], off offset:192
	global_store_dwordx4 v[180:181], v[28:31], off
	global_store_dwordx4 v[180:181], v[24:27], off offset:64
	global_store_dwordx4 v[180:181], v[20:23], off offset:128
	global_store_dwordx4 v[180:181], v[16:19], off offset:192
	global_store_dwordx4 v[182:183], v[12:15], off
	global_store_dwordx4 v[182:183], v[8:11], off offset:64
	global_store_dwordx4 v[182:183], v[4:7], off offset:128
	global_store_dwordx4 v[182:183], v[0:3], off offset:192
	s_cbranch_scc1 .LBB0_754
